# Gates and In1 GEMM epilogues: the 8 serialized row-sumsq loads (load-wait-load-wait) issued together into dead fragment VGPRs, one wait
# speedup vs baseline: 1.0058x; 1.0058x over previous
; template <int NP> __device__ __forceinline__ void row_scales(float (&rs)[2][4], const float* base, long row0, int fq, float inv_n) {
;     float t[2][4];
; #pragma unroll
;     for (int ai = 0; ai < 2; ++ai)
; #pragma unroll
;         for (int m = 0; m < 4; ++m) { const long row = row0 + ai * 128 + m * 16;
;             if (NP == 16) { const f32x4 v = *(const f32x4*)(base + row * 16 + 4 * fq); t[ai][m] = (v.x + v.y) + (v.z + v.w); }
;             else if (NP == 8) { const f32x2 v = *(const f32x2*)(base + row * 8 + 2 * fq); t[ai][m] = v.x + v.y; }
;             else t[ai][m] = base[row * 4 + fq]; }
; #pragma unroll
;     for (int ai = 0; ai < 2; ++ai)
; #pragma unroll
;         for (int m = 0; m < 4; ++m) rs[ai][m] = rsqrtf(red_fq(t[ai][m]) * inv_n + EPS);
;     __device__ __forceinline__ void operator()(AccT& acc, const Unit& u, int wr, int wc, int fr, int fq, LAS unsigned char*) const {
;         const long row0 = (long)u.pm * 256 + wr * 64 + fr;
;         const size_t tb = ((size_t)(u.pm * 12 + u.pn) * 8 + (wr * 4 + wc)) * 16; const int lane = fq * 16 + fr;
;         float rsa[2][4]; row_scales<16>(rsa, ssqx, row0, fq, 1.f / 1024.f);
.LBB0_335:
	s_ashr_i32 s1, s0, 31
	s_mul_i32 s8, s0, 12
	s_lshl_b64 s[0:1], s[0:1], 14
	v_lshl_add_u64 v[144:145], v[134:135], 0, s[0:1]
	global_load_dwordx4 v[140:143], v[144:145], off
	s_add_i32 s8, s8, s79
	s_ashr_i32 s9, s8, 31
	s_lshl_b64 s[12:13], s[8:9], 17
	s_movk_i32 s8, 0x2000
	v_add_co_u32_e32 v162, vcc, s8, v144
	s_mov_b32 s0, 0x358637bd
	s_nop 0
	v_addc_co_u32_e32 v163, vcc, 0, v145, vcc
	global_load_dwordx4 v[156:159], v[162:163], off offset:2048
	global_load_dwordx4 v[164:167], v[144:145], off offset:1024
	global_load_dwordx4 v[168:171], v[144:145], off offset:2048
	global_load_dwordx4 v[172:175], v[144:145], off offset:3072
	global_load_dwordx4 v[176:179], v[162:163], off
	global_load_dwordx4 v[180:183], v[162:163], off offset:1024
	global_load_dwordx4 v[184:187], v[162:163], off offset:3072
	s_mov_b32 s18, 0x3a800000
	s_movk_i32 s75, 0xc0
	s_mov_b32 s26, 0x18000
	s_waitcnt vmcnt(0)
	v_mov_b32_e32 v146, v141
	v_mov_b32_e32 v147, v142
	v_mov_b32_e32 v141, v143
	v_pk_add_f32 v[140:141], v[146:147], v[140:141]
	s_nop 0
	v_pk_add_f32 v[150:151], v[140:141], v[140:141] op_sel:[0,1] op_sel_hi:[1,0]
	v_mov_b64_e32 v[140:141], v[164:165]
	v_mov_b64_e32 v[142:143], v[166:167]
	v_mov_b32_e32 v146, v141
	v_mov_b32_e32 v147, v142
	v_mov_b32_e32 v141, v143
	v_pk_add_f32 v[140:141], v[146:147], v[140:141]
	s_nop 0
	v_pk_add_f32 v[160:161], v[140:141], v[140:141] op_sel:[0,1] op_sel_hi:[1,0]
	v_mov_b64_e32 v[140:141], v[168:169]
	v_mov_b64_e32 v[142:143], v[170:171]
	v_mov_b32_e32 v146, v141
	v_mov_b32_e32 v147, v142
	v_mov_b32_e32 v141, v143
	v_pk_add_f32 v[140:141], v[146:147], v[140:141]
	s_nop 0
	v_pk_add_f32 v[152:153], v[140:141], v[140:141] op_sel:[0,1] op_sel_hi:[1,0]
	v_mov_b64_e32 v[140:141], v[172:173]
	v_mov_b64_e32 v[142:143], v[174:175]
	v_mov_b32_e32 v146, v141
	v_mov_b32_e32 v147, v142
	v_mov_b32_e32 v141, v143
	v_pk_add_f32 v[140:141], v[146:147], v[140:141]
	s_nop 0
	v_pk_add_f32 v[148:149], v[140:141], v[140:141] op_sel:[0,1] op_sel_hi:[1,0]
	v_mov_b64_e32 v[140:141], v[176:177]
	v_mov_b64_e32 v[142:143], v[178:179]
	v_mov_b32_e32 v144, v141
	v_mov_b32_e32 v145, v142
	v_mov_b32_e32 v141, v143
	v_pk_add_f32 v[140:141], v[144:145], v[140:141]
	v_mov_b64_e32 v[144:145], v[180:181]
	v_mov_b64_e32 v[146:147], v[182:183]
	v_pk_add_f32 v[142:143], v[140:141], v[140:141] op_sel:[0,1] op_sel_hi:[1,0]
	v_mov_b32_e32 v140, v145
	v_mov_b32_e32 v141, v146
	v_mov_b32_e32 v145, v147
	v_pk_add_f32 v[140:141], v[140:141], v[144:145]
	s_nop 0
	v_pk_add_f32 v[146:147], v[140:141], v[140:141] op_sel:[0,1] op_sel_hi:[1,0]
	v_mov_b32_e32 v140, v157
	v_mov_b32_e32 v141, v158
	v_mov_b32_e32 v157, v159
	v_pk_add_f32 v[140:141], v[140:141], v[156:157]
	v_mov_b64_e32 v[156:157], v[184:185]
	v_mov_b64_e32 v[158:159], v[186:187]
	v_pk_add_f32 v[140:141], v[140:141], v[140:141] op_sel:[0,1] op_sel_hi:[1,0]
	v_mov_b32_e32 v144, v157
	v_mov_b32_e32 v141, v150
	s_nop 1
	v_permlane16_swap_b32_e32 v150, v141
	v_add_f32_e32 v151, v150, v141
	v_mov_b32_e32 v141, v160
	s_nop 1
	v_permlane16_swap_b32_e32 v160, v141
	v_mov_b32_e32 v145, v158
	v_mov_b32_e32 v157, v159
	v_add_f32_e32 v150, v160, v141
	v_pk_add_f32 v[144:145], v[144:145], v[156:157]
	v_mov_b32_e32 v157, v151
	v_mov_b32_e32 v156, v150
	s_nop 0
	v_permlane32_swap_b32_e32 v151, v157
	v_permlane32_swap_b32_e32 v150, v156
	v_pk_add_f32 v[156:157], v[150:151], v[156:157]
	v_mov_b64_e32 v[150:151], s[0:1]
	v_pk_fma_f32 v[156:157], v[156:157], s[18:19], v[150:151] op_sel_hi:[1,0,0]
	v_pk_add_f32 v[144:145], v[144:145], v[144:145] op_sel:[0,1] op_sel_hi:[1,0]
	v_mul_f32_e32 v141, 0x4b800000, v157
	v_cmp_gt_f32_e64 s[0:1], s33, v157
	v_cmp_gt_f32_e32 vcc, s33, v156
	s_nop 0
	v_cndmask_b32_e64 v141, v157, v141, s[0:1]
	v_rsq_f32_e32 v141, v141
	s_nop 0
	v_mul_f32_e32 v143, 0x45800000, v141
	v_cndmask_b32_e64 v149, v141, v143, s[0:1]
	v_mul_f32_e32 v141, 0x4b800000, v156
	v_cndmask_b32_e32 v141, v156, v141, vcc
	v_rsq_f32_e32 v141, v141
	s_nop 0
	v_mul_f32_e32 v143, 0x45800000, v141
	v_cndmask_b32_e32 v147, v141, v143, vcc
	v_mov_b32_e32 v141, v152
	s_nop 1
	v_permlane16_swap_b32_e32 v152, v141
	v_add_f32_e32 v153, v152, v141
	v_mov_b32_e32 v141, v148
	s_nop 1
	v_permlane16_swap_b32_e32 v148, v141
	v_add_f32_e32 v152, v148, v141
	v_mov_b32_e32 v157, v153
	v_mov_b32_e32 v156, v152
	s_nop 0
	v_permlane32_swap_b32_e32 v153, v157
	v_permlane32_swap_b32_e32 v152, v156
	v_pk_add_f32 v[152:153], v[152:153], v[156:157]
	s_nop 0
	v_pk_fma_f32 v[152:153], v[152:153], s[18:19], v[150:151] op_sel_hi:[1,0,0]
	s_nop 0
	v_mul_f32_e32 v141, 0x4b800000, v153
	v_cmp_gt_f32_e64 s[0:1], s33, v153
	v_cmp_gt_f32_e32 vcc, s33, v152
	s_nop 0
	v_cndmask_b32_e64 v141, v153, v141, s[0:1]
	v_rsq_f32_e32 v141, v141
	s_nop 0
	v_mul_f32_e32 v143, 0x45800000, v141
	v_cndmask_b32_e64 v148, v141, v143, s[0:1]
	v_mul_f32_e32 v141, 0x4b800000, v152
	v_cndmask_b32_e32 v141, v152, v141, vcc
	v_rsq_f32_e32 v141, v141
	s_nop 0
	v_mul_f32_e32 v143, 0x45800000, v141
	v_cndmask_b32_e32 v145, v141, v143, vcc
	v_mov_b32_e32 v141, v142
	s_nop 1
	v_permlane16_swap_b32_e32 v142, v141
	v_add_f32_e32 v143, v142, v141
	v_mov_b32_e32 v141, v146
	s_nop 1
	v_permlane16_swap_b32_e32 v146, v141
	v_add_f32_e32 v142, v146, v141
	v_mov_b32_e32 v153, v143
	v_mov_b32_e32 v152, v142
	s_nop 0
	v_permlane32_swap_b32_e32 v143, v153
	v_permlane32_swap_b32_e32 v142, v152
	v_pk_add_f32 v[142:143], v[142:143], v[152:153]
	s_nop 0
	v_pk_fma_f32 v[142:143], v[142:143], s[18:19], v[150:151] op_sel_hi:[1,0,0]
	s_nop 0
	v_mul_f32_e32 v141, 0x4b800000, v143
	v_cmp_gt_f32_e64 s[0:1], s33, v143
	v_cmp_gt_f32_e32 vcc, s33, v142
	s_nop 0
	v_cndmask_b32_e64 v141, v143, v141, s[0:1]
; __device__ __forceinline__ unsigned pk2(float lo, float hi) { f32x2 v = {lo, hi}; bf16x2_t b = __builtin_convertvector(v, bf16x2_t); return __builtin_bit_cast(unsigned, b); }
; #define SG_(t) __builtin_amdgcn_rcpf(1.f + __builtin_amdgcn_exp2f(min2f(t, 19.931568f)))
;     __device__ __forceinline__ void operator()(AccT& acc, const Unit& u, int wr, int wc, int fr, int fq, LAS unsigned char*) const {
;     ...
; #pragma unroll
;         for (int ai = 0; ai < 2; ++ai)
; #pragma unroll
;             for (int m = 0; m < 4; ++m) {
;                 const float rs = rsa[ai][m] * -LOG2E;
;     ...
; #pragma unroll
;                 for (int bj = 0; bj < 2; ++bj) { const f32x4 v0 = acc[ai][bj][m][0] * rs, v1 = acc[ai][bj][m][1] * rs; u32x4 w;
;                     w.x = pk2(SG_(v0.x), SG_(v0.y)); w.y = pk2(SG_(v0.z), SG_(v0.w)); w.z = pk2(SG_(v1.x), SG_(v1.y)); w.w = pk2(SG_(v1.z), SG_(v1.w));
;     ...
;                     *(u32x4*)(gates + ((tb + (ai * 4 + m) * 2 + bj) * 64 + lane) * 8) = w; }
;             }
	v_rsq_f32_e32 v141, v141
	s_nop 0
	v_mul_f32_e32 v143, 0x45800000, v141
	v_cndmask_b32_e64 v143, v141, v143, s[0:1]
	v_mul_f32_e32 v141, 0x4b800000, v142
	v_cndmask_b32_e32 v141, v142, v141, vcc
	v_rsq_f32_e32 v141, v141
	s_nop 0
	v_mul_f32_e32 v142, 0x45800000, v141
	v_cndmask_b32_e32 v142, v141, v142, vcc
	v_mov_b32_e32 v141, v140
	s_nop 1
	v_permlane16_swap_b32_e32 v140, v141
	v_add_f32_e32 v141, v140, v141
	v_mov_b32_e32 v140, v144
	s_nop 1
	v_permlane16_swap_b32_e32 v144, v140
	v_add_f32_e32 v140, v144, v140
	v_mov_b32_e32 v153, v141
	v_mov_b32_e32 v152, v140
	s_nop 0
	v_permlane32_swap_b32_e32 v141, v153
	v_permlane32_swap_b32_e32 v140, v152
	v_pk_add_f32 v[140:141], v[140:141], v[152:153]
	s_nop 0
	v_pk_fma_f32 v[140:141], v[140:141], s[18:19], v[150:151] op_sel_hi:[1,0,0]
	s_nop 0
	v_mul_f32_e32 v144, 0x4b800000, v141
	v_cmp_gt_f32_e64 s[0:1], s33, v141
	v_cmp_gt_f32_e32 vcc, s33, v140
	s_nop 0
	v_cndmask_b32_e64 v141, v141, v144, s[0:1]
	v_rsq_f32_e32 v141, v141
	s_nop 0
	v_mul_f32_e32 v144, 0x45800000, v141
	v_cndmask_b32_e64 v141, v141, v144, s[0:1]
	v_mul_f32_e32 v144, 0x4b800000, v140
	v_cndmask_b32_e32 v140, v140, v144, vcc
	v_rsq_f32_e32 v140, v140
	s_add_u32 s0, s2, s12
	s_addc_u32 s1, s55, s13
	v_mul_f32_e32 v144, 0x45800000, v140
	v_cndmask_b32_e32 v140, v140, v144, vcc
	v_mul_f32_e32 v144, 0xbfb8aa3b, v149
	v_pk_mul_f32 v[126:127], v[126:127], v[144:145] op_sel_hi:[1,0]
	v_pk_mul_f32 v[150:151], v[124:125], v[144:145] op_sel_hi:[1,0]
	v_min_f32_e32 v124, v126, v246
	v_min_f32_e32 v125, v127, v246
	v_pk_mul_f32 v[122:123], v[122:123], v[144:145] op_sel_hi:[1,0]
	v_exp_f32_e32 v124, v124
	v_exp_f32_e32 v125, v125
	v_pk_mul_f32 v[128:129], v[128:129], v[144:145] op_sel_hi:[1,0]
	v_min_f32_e32 v122, v122, v246
	v_add_f32_e32 v124, 1.0, v124
	v_add_f32_e32 v125, 1.0, v125
	v_rcp_f32_e32 v124, v124
	v_rcp_f32_e32 v125, v125
	v_min_f32_e32 v126, v129, v246
	v_min_f32_e32 v123, v123, v246
	v_exp_f32_e32 v122, v122
	v_cvt_pk_bf16_f32 v124, v124, v125
	v_min_f32_e32 v125, v128, v246
	v_exp_f32_e32 v126, v126
	v_exp_f32_e32 v125, v125
	v_exp_f32_e32 v123, v123
	v_add_f32_e32 v122, 1.0, v122
	v_add_f32_e32 v126, 1.0, v126
	v_add_f32_e32 v125, 1.0, v125
	v_add_f32_e32 v123, 1.0, v123
	v_rcp_f32_e32 v125, v125
	v_rcp_f32_e32 v126, v126
	v_rcp_f32_e32 v122, v122
	v_rcp_f32_e32 v123, v123
	v_pk_mul_f32 v[118:119], v[118:119], v[144:145] op_sel_hi:[1,0]
	v_cvt_pk_bf16_f32 v125, v125, v126
	v_pk_mul_f32 v[120:121], v[120:121], v[144:145] op_sel_hi:[1,0]
	v_cvt_pk_bf16_f32 v126, v122, v123
	v_min_f32_e32 v122, v150, v246
	v_min_f32_e32 v123, v151, v246
	s_nop 0
	v_exp_f32_e32 v122, v122
	v_exp_f32_e32 v123, v123
	v_add_f32_e32 v122, 1.0, v122
	v_add_f32_e32 v123, 1.0, v123
	v_rcp_f32_e32 v122, v122
	v_rcp_f32_e32 v123, v123
	s_nop 0
	v_cvt_pk_bf16_f32 v127, v122, v123
	global_store_dwordx4 v0, v[124:127], s[0:1]
	v_lshl_add_u64 v[122:123], s[0:1], 0, v[0:1]
	s_nop 0
	v_pk_mul_f32 v[124:125], v[116:117], v[144:145] op_sel_hi:[1,0]
	v_pk_mul_f32 v[116:117], v[114:115], v[144:145] op_sel_hi:[1,0]
	v_min_f32_e32 v114, v118, v246
	v_min_f32_e32 v115, v119, v246
	v_min_f32_e32 v118, v121, v246
	s_nop 0
	v_exp_f32_e32 v114, v114
	v_exp_f32_e32 v115, v115
	v_min_f32_e32 v116, v116, v246
	v_min_f32_e32 v117, v117, v246
	v_add_f32_e32 v114, 1.0, v114
	v_add_f32_e32 v115, 1.0, v115
	v_rcp_f32_e32 v114, v114
	v_rcp_f32_e32 v115, v115
	v_exp_f32_e32 v118, v118
	v_exp_f32_e32 v116, v116
	v_exp_f32_e32 v117, v117
	v_cvt_pk_bf16_f32 v114, v114, v115
	v_min_f32_e32 v115, v120, v246
	v_add_f32_e32 v118, 1.0, v118
	v_exp_f32_e32 v115, v115
	v_add_f32_e32 v116, 1.0, v116
	v_add_f32_e32 v117, 1.0, v117
	v_rcp_f32_e32 v118, v118
	v_add_f32_e32 v115, 1.0, v115
	v_rcp_f32_e32 v115, v115
	v_rcp_f32_e32 v116, v116
	v_rcp_f32_e32 v117, v117
	v_cvt_pk_bf16_f32 v115, v115, v118
	v_min_f32_e32 v118, v125, v246
	v_cvt_pk_bf16_f32 v116, v116, v117
	v_min_f32_e32 v117, v124, v246
	v_exp_f32_e32 v118, v118
	v_exp_f32_e32 v117, v117
	v_add_f32_e32 v118, 1.0, v118
	v_add_f32_e32 v117, 1.0, v117
	v_rcp_f32_e32 v117, v117
	v_rcp_f32_e32 v118, v118
	s_nop 0
	v_cvt_pk_bf16_f32 v117, v117, v118
	global_store_dwordx4 v0, v[114:117], s[0:1] offset:1024
	s_nop 1
	v_mul_f32_e32 v114, 0xbfb8aa3b, v147
	v_pk_mul_f32 v[110:111], v[110:111], v[114:115] op_sel_hi:[1,0]
	v_pk_mul_f32 v[116:117], v[108:109], v[114:115] op_sel_hi:[1,0]
	v_pk_mul_f32 v[108:109], v[106:107], v[114:115] op_sel_hi:[1,0]
	v_min_f32_e32 v106, v110, v246
	v_min_f32_e32 v107, v111, v246
	v_pk_mul_f32 v[112:113], v[112:113], v[114:115] op_sel_hi:[1,0]
	v_exp_f32_e32 v106, v106
	v_exp_f32_e32 v107, v107
	v_min_f32_e32 v110, v113, v246
	v_min_f32_e32 v108, v108, v246
	v_add_f32_e32 v106, 1.0, v106
	v_add_f32_e32 v107, 1.0, v107
	v_rcp_f32_e32 v106, v106
	v_rcp_f32_e32 v107, v107
	v_min_f32_e32 v109, v109, v246
	v_exp_f32_e32 v110, v110
	v_exp_f32_e32 v108, v108
	v_cvt_pk_bf16_f32 v106, v106, v107
	v_min_f32_e32 v107, v112, v246
	v_exp_f32_e32 v109, v109
	v_exp_f32_e32 v107, v107
	v_add_f32_e32 v110, 1.0, v110
	v_add_f32_e32 v108, 1.0, v108
	v_add_f32_e32 v109, 1.0, v109
	v_add_f32_e32 v107, 1.0, v107
	v_rcp_f32_e32 v107, v107
	v_rcp_f32_e32 v110, v110
	v_rcp_f32_e32 v108, v108
	v_rcp_f32_e32 v109, v109
	v_pk_mul_f32 v[102:103], v[102:103], v[114:115] op_sel_hi:[1,0]
	v_cvt_pk_bf16_f32 v107, v107, v110
	v_min_f32_e32 v110, v117, v246
	v_cvt_pk_bf16_f32 v108, v108, v109
	v_min_f32_e32 v109, v116, v246
	v_exp_f32_e32 v110, v110
	v_exp_f32_e32 v109, v109
	v_pk_mul_f32 v[104:105], v[104:105], v[114:115] op_sel_hi:[1,0]
	v_add_f32_e32 v110, 1.0, v110
	v_add_f32_e32 v109, 1.0, v109
	v_rcp_f32_e32 v109, v109
; __device__ __forceinline__ unsigned pk2(float lo, float hi) { f32x2 v = {lo, hi}; bf16x2_t b = __builtin_convertvector(v, bf16x2_t); return __builtin_bit_cast(unsigned, b); }
; #define SG_(t) __builtin_amdgcn_rcpf(1.f + __builtin_amdgcn_exp2f(min2f(t, 19.931568f)))
;     __device__ __forceinline__ void operator()(AccT& acc, const Unit& u, int wr, int wc, int fr, int fq, LAS unsigned char*) const {
;     ...
; #pragma unroll
;         for (int ai = 0; ai < 2; ++ai)
; #pragma unroll
;             for (int m = 0; m < 4; ++m) {
;                 const float rs = rsa[ai][m] * -LOG2E;
;     ...
; #pragma unroll
;                 for (int bj = 0; bj < 2; ++bj) { const f32x4 v0 = acc[ai][bj][m][0] * rs, v1 = acc[ai][bj][m][1] * rs; u32x4 w;
;                     w.x = pk2(SG_(v0.x), SG_(v0.y)); w.y = pk2(SG_(v0.z), SG_(v0.w)); w.z = pk2(SG_(v1.x), SG_(v1.y)); w.w = pk2(SG_(v1.z), SG_(v1.w));
;     ...
;                     *(u32x4*)(gates + ((tb + (ai * 4 + m) * 2 + bj) * 64 + lane) * 8) = w; }
;             }
	v_rcp_f32_e32 v110, v110
	s_nop 0
	v_cvt_pk_bf16_f32 v109, v109, v110
	global_store_dwordx4 v0, v[106:109], s[0:1] offset:2048
	s_nop 1
	v_pk_mul_f32 v[106:107], v[100:101], v[114:115] op_sel_hi:[1,0]
	v_pk_mul_f32 v[100:101], v[98:99], v[114:115] op_sel_hi:[1,0]
	v_min_f32_e32 v98, v102, v246
	v_min_f32_e32 v99, v103, v246
	v_min_f32_e32 v102, v105, v246
	s_nop 0
	v_exp_f32_e32 v98, v98
	v_exp_f32_e32 v99, v99
	v_min_f32_e32 v100, v100, v246
	v_min_f32_e32 v101, v101, v246
	v_add_f32_e32 v98, 1.0, v98
	v_add_f32_e32 v99, 1.0, v99
	v_rcp_f32_e32 v98, v98
	v_rcp_f32_e32 v99, v99
	v_exp_f32_e32 v102, v102
	v_exp_f32_e32 v100, v100
	v_exp_f32_e32 v101, v101
	v_cvt_pk_bf16_f32 v98, v98, v99
	v_min_f32_e32 v99, v104, v246
	v_add_f32_e32 v102, 1.0, v102
	v_exp_f32_e32 v99, v99
	v_add_f32_e32 v100, 1.0, v100
	v_add_f32_e32 v101, 1.0, v101
	v_rcp_f32_e32 v102, v102
	v_add_f32_e32 v99, 1.0, v99
	v_rcp_f32_e32 v99, v99
	v_rcp_f32_e32 v100, v100
	v_rcp_f32_e32 v101, v101
	v_cvt_pk_bf16_f32 v99, v99, v102
	v_min_f32_e32 v102, v107, v246
	v_cvt_pk_bf16_f32 v100, v100, v101
	v_min_f32_e32 v101, v106, v246
	v_exp_f32_e32 v102, v102
	v_exp_f32_e32 v101, v101
	v_add_f32_e32 v102, 1.0, v102
	v_add_f32_e32 v101, 1.0, v101
	v_rcp_f32_e32 v101, v101
	v_rcp_f32_e32 v102, v102
	s_nop 0
	v_cvt_pk_bf16_f32 v101, v101, v102
	global_store_dwordx4 v0, v[98:101], s[0:1] offset:3072
	s_movk_i32 s0, 0x1000
	s_nop 0
	v_mul_f32_e32 v98, 0xbfb8aa3b, v148
	v_pk_mul_f32 v[94:95], v[94:95], v[98:99] op_sel_hi:[1,0]
	v_pk_mul_f32 v[96:97], v[96:97], v[98:99] op_sel_hi:[1,0]
	v_min_f32_e32 v94, v94, v246
	v_min_f32_e32 v95, v95, v246
	v_pk_mul_f32 v[90:91], v[90:91], v[98:99] op_sel_hi:[1,0]
	v_exp_f32_e32 v94, v94
	v_exp_f32_e32 v95, v95
	v_min_f32_e32 v90, v90, v246
	v_min_f32_e32 v91, v91, v246
	v_add_f32_e32 v94, 1.0, v94
	v_add_f32_e32 v95, 1.0, v95
	v_rcp_f32_e32 v94, v94
	v_rcp_f32_e32 v95, v95
	v_exp_f32_e32 v90, v90
	v_exp_f32_e32 v91, v91
	v_pk_mul_f32 v[92:93], v[92:93], v[98:99] op_sel_hi:[1,0]
	v_cvt_pk_bf16_f32 v94, v94, v95
	v_min_f32_e32 v95, v96, v246
	v_min_f32_e32 v96, v97, v246
	v_add_f32_e32 v90, 1.0, v90
	v_exp_f32_e32 v95, v95
	v_exp_f32_e32 v96, v96
	v_add_f32_e32 v91, 1.0, v91
	v_rcp_f32_e32 v90, v90
	v_add_f32_e32 v95, 1.0, v95
	v_add_f32_e32 v96, 1.0, v96
	v_rcp_f32_e32 v95, v95
	v_rcp_f32_e32 v96, v96
	v_rcp_f32_e32 v91, v91
	v_pk_mul_f32 v[86:87], v[86:87], v[98:99] op_sel_hi:[1,0]
	v_pk_mul_f32 v[88:89], v[88:89], v[98:99] op_sel_hi:[1,0]
	v_cvt_pk_bf16_f32 v95, v95, v96
	v_cvt_pk_bf16_f32 v96, v90, v91
	v_min_f32_e32 v90, v92, v246
	v_min_f32_e32 v91, v93, v246
	v_add_co_u32_e32 v92, vcc, s0, v122
	v_exp_f32_e32 v90, v90
	v_exp_f32_e32 v91, v91
	v_addc_co_u32_e32 v93, vcc, 0, v123, vcc
	v_add_f32_e32 v90, 1.0, v90
	v_add_f32_e32 v91, 1.0, v91
	v_rcp_f32_e32 v90, v90
	v_rcp_f32_e32 v91, v91
	s_movk_i32 s0, 0x3000
	v_cvt_pk_bf16_f32 v97, v90, v91
	v_add_co_u32_e32 v90, vcc, s8, v122
	s_nop 1
	v_addc_co_u32_e32 v91, vcc, 0, v123, vcc
	global_store_dwordx4 v[90:91], v[94:97], off offset:-4096
	s_nop 1
	v_pk_mul_f32 v[94:95], v[84:85], v[98:99] op_sel_hi:[1,0]
	v_pk_mul_f32 v[84:85], v[82:83], v[98:99] op_sel_hi:[1,0]
	v_min_f32_e32 v82, v86, v246
	v_min_f32_e32 v83, v87, v246
	v_min_f32_e32 v86, v89, v246
	s_nop 0
	v_exp_f32_e32 v82, v82
	v_exp_f32_e32 v83, v83
	v_min_f32_e32 v84, v84, v246
	v_min_f32_e32 v85, v85, v246
	v_add_f32_e32 v82, 1.0, v82
	v_add_f32_e32 v83, 1.0, v83
	v_rcp_f32_e32 v82, v82
	v_rcp_f32_e32 v83, v83
	v_exp_f32_e32 v86, v86
	v_exp_f32_e32 v84, v84
	v_exp_f32_e32 v85, v85
	v_cvt_pk_bf16_f32 v82, v82, v83
	v_min_f32_e32 v83, v88, v246
	v_add_f32_e32 v86, 1.0, v86
	v_exp_f32_e32 v83, v83
	v_add_f32_e32 v84, 1.0, v84
	v_add_f32_e32 v85, 1.0, v85
	v_rcp_f32_e32 v86, v86
	v_add_f32_e32 v83, 1.0, v83
	v_rcp_f32_e32 v83, v83
	v_rcp_f32_e32 v84, v84
	v_rcp_f32_e32 v85, v85
	v_cvt_pk_bf16_f32 v83, v83, v86
	v_min_f32_e32 v86, v95, v246
	v_cvt_pk_bf16_f32 v84, v84, v85
	v_min_f32_e32 v85, v94, v246
	v_exp_f32_e32 v86, v86
	v_exp_f32_e32 v85, v85
	v_add_f32_e32 v86, 1.0, v86
	v_add_f32_e32 v85, 1.0, v85
	v_rcp_f32_e32 v85, v85
	v_rcp_f32_e32 v86, v86
	s_nop 0
	v_cvt_pk_bf16_f32 v85, v85, v86
	global_store_dwordx4 v[92:93], v[82:85], off offset:1024
	s_nop 1
	v_mul_f32_e32 v82, 0xbfb8aa3b, v145
	v_pk_mul_f32 v[78:79], v[78:79], v[82:83] op_sel_hi:[1,0]
	v_pk_mul_f32 v[84:85], v[76:77], v[82:83] op_sel_hi:[1,0]
	v_pk_mul_f32 v[76:77], v[74:75], v[82:83] op_sel_hi:[1,0]
	v_min_f32_e32 v74, v78, v246
	v_min_f32_e32 v75, v79, v246
	v_pk_mul_f32 v[80:81], v[80:81], v[82:83] op_sel_hi:[1,0]
	v_exp_f32_e32 v74, v74
	v_exp_f32_e32 v75, v75
	v_min_f32_e32 v78, v81, v246
	v_min_f32_e32 v76, v76, v246
	v_add_f32_e32 v74, 1.0, v74
	v_add_f32_e32 v75, 1.0, v75
	v_rcp_f32_e32 v74, v74
	v_rcp_f32_e32 v75, v75
	v_min_f32_e32 v77, v77, v246
	v_exp_f32_e32 v78, v78
	v_exp_f32_e32 v76, v76
	v_cvt_pk_bf16_f32 v74, v74, v75
	v_min_f32_e32 v75, v80, v246
	v_exp_f32_e32 v77, v77
	v_exp_f32_e32 v75, v75
	v_add_f32_e32 v78, 1.0, v78
	v_add_f32_e32 v76, 1.0, v76
	v_add_f32_e32 v77, 1.0, v77
	v_add_f32_e32 v75, 1.0, v75
	v_rcp_f32_e32 v75, v75
	v_rcp_f32_e32 v78, v78
	v_rcp_f32_e32 v76, v76
	v_rcp_f32_e32 v77, v77
	v_pk_mul_f32 v[70:71], v[70:71], v[82:83] op_sel_hi:[1,0]
	v_cvt_pk_bf16_f32 v75, v75, v78
	v_min_f32_e32 v78, v85, v246
	v_cvt_pk_bf16_f32 v76, v76, v77
	v_min_f32_e32 v77, v84, v246
	v_exp_f32_e32 v78, v78
	v_exp_f32_e32 v77, v77
	v_pk_mul_f32 v[72:73], v[72:73], v[82:83] op_sel_hi:[1,0]
	v_add_f32_e32 v78, 1.0, v78
	v_add_f32_e32 v77, 1.0, v77
	v_rcp_f32_e32 v77, v77
	v_rcp_f32_e32 v78, v78
	s_nop 0
	v_cvt_pk_bf16_f32 v77, v77, v78
; __device__ __forceinline__ unsigned pk2(float lo, float hi) { f32x2 v = {lo, hi}; bf16x2_t b = __builtin_convertvector(v, bf16x2_t); return __builtin_bit_cast(unsigned, b); }
; #define SG_(t) __builtin_amdgcn_rcpf(1.f + __builtin_amdgcn_exp2f(min2f(t, 19.931568f)))
;     __device__ __forceinline__ void operator()(AccT& acc, const Unit& u, int wr, int wc, int fr, int fq, LAS unsigned char*) const {
;     ...
; #pragma unroll
;         for (int ai = 0; ai < 2; ++ai)
; #pragma unroll
;             for (int m = 0; m < 4; ++m) {
;                 const float rs = rsa[ai][m] * -LOG2E;
;     ...
; #pragma unroll
;                 for (int bj = 0; bj < 2; ++bj) { const f32x4 v0 = acc[ai][bj][m][0] * rs, v1 = acc[ai][bj][m][1] * rs; u32x4 w;
;                     w.x = pk2(SG_(v0.x), SG_(v0.y)); w.y = pk2(SG_(v0.z), SG_(v0.w)); w.z = pk2(SG_(v1.x), SG_(v1.y)); w.w = pk2(SG_(v1.z), SG_(v1.w));
;     ...
;                     *(u32x4*)(gates + ((tb + (ai * 4 + m) * 2 + bj) * 64 + lane) * 8) = w; }
;             }
	global_store_dwordx4 v[92:93], v[74:77], off offset:2048
	s_nop 1
	v_pk_mul_f32 v[74:75], v[68:69], v[82:83] op_sel_hi:[1,0]
	v_pk_mul_f32 v[68:69], v[66:67], v[82:83] op_sel_hi:[1,0]
	v_min_f32_e32 v66, v70, v246
	v_min_f32_e32 v67, v71, v246
	v_min_f32_e32 v70, v73, v246
	s_nop 0
	v_exp_f32_e32 v66, v66
	v_exp_f32_e32 v67, v67
	v_min_f32_e32 v68, v68, v246
	v_min_f32_e32 v69, v69, v246
	v_add_f32_e32 v66, 1.0, v66
	v_add_f32_e32 v67, 1.0, v67
	v_rcp_f32_e32 v66, v66
	v_rcp_f32_e32 v67, v67
	v_exp_f32_e32 v70, v70
	v_exp_f32_e32 v68, v68
	v_exp_f32_e32 v69, v69
	v_cvt_pk_bf16_f32 v66, v66, v67
	v_min_f32_e32 v67, v72, v246
	v_add_f32_e32 v70, 1.0, v70
	v_exp_f32_e32 v67, v67
	v_add_f32_e32 v68, 1.0, v68
	v_add_f32_e32 v69, 1.0, v69
	v_rcp_f32_e32 v70, v70
	v_add_f32_e32 v67, 1.0, v67
	v_rcp_f32_e32 v67, v67
	v_rcp_f32_e32 v68, v68
	v_rcp_f32_e32 v69, v69
	v_cvt_pk_bf16_f32 v67, v67, v70
	v_min_f32_e32 v70, v75, v246
	v_cvt_pk_bf16_f32 v68, v68, v69
	v_min_f32_e32 v69, v74, v246
	v_exp_f32_e32 v70, v70
	v_exp_f32_e32 v69, v69
	v_add_f32_e32 v70, 1.0, v70
	v_add_f32_e32 v69, 1.0, v69
	v_rcp_f32_e32 v69, v69
	v_rcp_f32_e32 v70, v70
	s_nop 0
	v_cvt_pk_bf16_f32 v69, v69, v70
	global_store_dwordx4 v[92:93], v[66:69], off offset:3072
	s_nop 1
	v_mul_f32_e32 v66, 0xbfb8aa3b, v143
	v_pk_mul_f32 v[62:63], v[62:63], v[66:67] op_sel_hi:[1,0]
	v_pk_mul_f32 v[68:69], v[60:61], v[66:67] op_sel_hi:[1,0]
	v_pk_mul_f32 v[60:61], v[58:59], v[66:67] op_sel_hi:[1,0]
	v_min_f32_e32 v58, v62, v246
	v_min_f32_e32 v59, v63, v246
	v_pk_mul_f32 v[64:65], v[64:65], v[66:67] op_sel_hi:[1,0]
	v_exp_f32_e32 v58, v58
	v_exp_f32_e32 v59, v59
	v_min_f32_e32 v62, v65, v246
	v_min_f32_e32 v60, v60, v246
	v_add_f32_e32 v58, 1.0, v58
	v_add_f32_e32 v59, 1.0, v59
	v_rcp_f32_e32 v58, v58
	v_rcp_f32_e32 v59, v59
	v_min_f32_e32 v61, v61, v246
	v_exp_f32_e32 v62, v62
	v_exp_f32_e32 v60, v60
	v_cvt_pk_bf16_f32 v58, v58, v59
	v_min_f32_e32 v59, v64, v246
	v_exp_f32_e32 v61, v61
	v_exp_f32_e32 v59, v59
	v_add_f32_e32 v62, 1.0, v62
	v_add_f32_e32 v60, 1.0, v60
	v_add_f32_e32 v61, 1.0, v61
	v_add_f32_e32 v59, 1.0, v59
	v_rcp_f32_e32 v59, v59
	v_rcp_f32_e32 v62, v62
	v_rcp_f32_e32 v60, v60
	v_rcp_f32_e32 v61, v61
	v_pk_mul_f32 v[54:55], v[54:55], v[66:67] op_sel_hi:[1,0]
	v_cvt_pk_bf16_f32 v59, v59, v62
	v_min_f32_e32 v62, v69, v246
	v_cvt_pk_bf16_f32 v60, v60, v61
	v_min_f32_e32 v61, v68, v246
	v_exp_f32_e32 v62, v62
	v_exp_f32_e32 v61, v61
	v_pk_mul_f32 v[56:57], v[56:57], v[66:67] op_sel_hi:[1,0]
	v_add_f32_e32 v62, 1.0, v62
	v_add_f32_e32 v61, 1.0, v61
	v_rcp_f32_e32 v61, v61
	v_rcp_f32_e32 v62, v62
	s_nop 0
	v_cvt_pk_bf16_f32 v61, v61, v62
	global_store_dwordx4 v[90:91], v[58:61], off
	s_nop 1
	v_pk_mul_f32 v[58:59], v[52:53], v[66:67] op_sel_hi:[1,0]
	v_pk_mul_f32 v[52:53], v[50:51], v[66:67] op_sel_hi:[1,0]
	v_min_f32_e32 v50, v54, v246
	v_min_f32_e32 v51, v55, v246
	v_min_f32_e32 v54, v57, v246
	s_nop 0
	v_exp_f32_e32 v50, v50
	v_exp_f32_e32 v51, v51
	v_min_f32_e32 v52, v52, v246
	v_min_f32_e32 v53, v53, v246
	v_add_f32_e32 v50, 1.0, v50
	v_add_f32_e32 v51, 1.0, v51
	v_rcp_f32_e32 v50, v50
	v_rcp_f32_e32 v51, v51
	v_exp_f32_e32 v54, v54
	v_exp_f32_e32 v52, v52
	v_exp_f32_e32 v53, v53
	v_cvt_pk_bf16_f32 v50, v50, v51
	v_min_f32_e32 v51, v56, v246
	v_add_f32_e32 v54, 1.0, v54
	v_exp_f32_e32 v51, v51
	v_add_f32_e32 v52, 1.0, v52
	v_add_f32_e32 v53, 1.0, v53
	v_rcp_f32_e32 v54, v54
	v_add_f32_e32 v51, 1.0, v51
	v_rcp_f32_e32 v51, v51
	v_rcp_f32_e32 v52, v52
	v_rcp_f32_e32 v53, v53
	v_cvt_pk_bf16_f32 v51, v51, v54
	v_min_f32_e32 v54, v59, v246
	v_cvt_pk_bf16_f32 v52, v52, v53
	v_min_f32_e32 v53, v58, v246
	v_exp_f32_e32 v54, v54
	v_exp_f32_e32 v53, v53
	v_add_f32_e32 v54, 1.0, v54
	v_add_f32_e32 v53, 1.0, v53
	v_rcp_f32_e32 v53, v53
	v_rcp_f32_e32 v54, v54
	s_nop 0
	v_cvt_pk_bf16_f32 v53, v53, v54
	global_store_dwordx4 v[90:91], v[50:53], off offset:1024
	s_nop 1
	v_mul_f32_e32 v50, 0xbfb8aa3b, v142
	v_pk_mul_f32 v[46:47], v[46:47], v[50:51] op_sel_hi:[1,0]
	v_pk_mul_f32 v[52:53], v[44:45], v[50:51] op_sel_hi:[1,0]
	v_pk_mul_f32 v[44:45], v[42:43], v[50:51] op_sel_hi:[1,0]
	v_min_f32_e32 v42, v46, v246
	v_min_f32_e32 v43, v47, v246
	v_pk_mul_f32 v[48:49], v[48:49], v[50:51] op_sel_hi:[1,0]
	v_exp_f32_e32 v42, v42
	v_exp_f32_e32 v43, v43
	v_min_f32_e32 v46, v49, v246
	v_min_f32_e32 v44, v44, v246
	v_add_f32_e32 v42, 1.0, v42
	v_add_f32_e32 v43, 1.0, v43
	v_rcp_f32_e32 v42, v42
	v_rcp_f32_e32 v43, v43
	v_min_f32_e32 v45, v45, v246
	v_exp_f32_e32 v46, v46
	v_exp_f32_e32 v44, v44
	v_cvt_pk_bf16_f32 v42, v42, v43
	v_min_f32_e32 v43, v48, v246
	v_exp_f32_e32 v45, v45
	v_exp_f32_e32 v43, v43
	v_add_f32_e32 v46, 1.0, v46
	v_add_f32_e32 v44, 1.0, v44
	v_add_f32_e32 v45, 1.0, v45
	v_add_f32_e32 v43, 1.0, v43
	v_rcp_f32_e32 v43, v43
	v_rcp_f32_e32 v46, v46
	v_rcp_f32_e32 v44, v44
	v_rcp_f32_e32 v45, v45
	v_pk_mul_f32 v[38:39], v[38:39], v[50:51] op_sel_hi:[1,0]
	v_cvt_pk_bf16_f32 v43, v43, v46
	v_min_f32_e32 v46, v53, v246
	v_cvt_pk_bf16_f32 v44, v44, v45
	v_min_f32_e32 v45, v52, v246
	v_exp_f32_e32 v46, v46
	v_exp_f32_e32 v45, v45
	v_pk_mul_f32 v[40:41], v[40:41], v[50:51] op_sel_hi:[1,0]
	v_add_f32_e32 v46, 1.0, v46
	v_add_f32_e32 v45, 1.0, v45
	v_rcp_f32_e32 v45, v45
	v_rcp_f32_e32 v46, v46
	s_nop 0
	v_cvt_pk_bf16_f32 v45, v45, v46
	global_store_dwordx4 v[90:91], v[42:45], off offset:2048
	s_nop 1
	v_pk_mul_f32 v[42:43], v[36:37], v[50:51] op_sel_hi:[1,0]
	v_pk_mul_f32 v[36:37], v[34:35], v[50:51] op_sel_hi:[1,0]
	v_min_f32_e32 v34, v38, v246
	v_min_f32_e32 v35, v39, v246
	v_min_f32_e32 v38, v41, v246
	s_nop 0
	v_exp_f32_e32 v34, v34
	v_exp_f32_e32 v35, v35
	v_min_f32_e32 v36, v36, v246
; __device__ __forceinline__ unsigned pk2(float lo, float hi) { f32x2 v = {lo, hi}; bf16x2_t b = __builtin_convertvector(v, bf16x2_t); return __builtin_bit_cast(unsigned, b); }
; #define PG8_BAR __builtin_amdgcn_s_barrier()
; #define SG_(t) __builtin_amdgcn_rcpf(1.f + __builtin_amdgcn_exp2f(min2f(t, 19.931568f)))
; template <class Epi>
; __device__ __forceinline__ void gemm_phase(LAS unsigned char* lds, const Gemm g, const Sched& S, const Epi& E) {
;     ...
;         if (wr == 0) PG8_BAR;
;         E(acc, cur, wr, wc, fr, fq, lds + STAGE_BYTES);
;         if (!has_next) break;
;         if constexpr (!Epi::KEEP_ACC) {
; #pragma unroll
;         for (int a = 0; a < 2; ++a)
; #pragma unroll
;             for (int b = 0; b < 2; ++b)
; #pragma unroll
;                 for (int m = 0; m < 4; ++m)
; #pragma unroll
;                     for (int n = 0; n < 2; ++n) acc[a][b][m][n] = (f32x4){0.f, 0.f, 0.f, 0.f};
;         }
;         cur = nxt; cA = nA; cB = nB; ++ui; csp = nsp; chA = nhA;
;         if (wr == 1) PG8_BAR;
;     __device__ __forceinline__ void operator()(AccT& acc, const Unit& u, int wr, int wc, int fr, int fq, LAS unsigned char*) const {
;     ...
; #pragma unroll
;         for (int ai = 0; ai < 2; ++ai)
; #pragma unroll
;             for (int m = 0; m < 4; ++m) {
;                 const float rs = rsa[ai][m] * -LOG2E;
;     ...
; #pragma unroll
;                 for (int bj = 0; bj < 2; ++bj) { const f32x4 v0 = acc[ai][bj][m][0] * rs, v1 = acc[ai][bj][m][1] * rs; u32x4 w;
;                     w.x = pk2(SG_(v0.x), SG_(v0.y)); w.y = pk2(SG_(v0.z), SG_(v0.w)); w.z = pk2(SG_(v1.x), SG_(v1.y)); w.w = pk2(SG_(v1.z), SG_(v1.w));
;     ...
;                     *(u32x4*)(gates + ((tb + (ai * 4 + m) * 2 + bj) * 64 + lane) * 8) = w; }
;             }
	v_min_f32_e32 v37, v37, v246
	v_add_f32_e32 v34, 1.0, v34
	v_add_f32_e32 v35, 1.0, v35
	v_rcp_f32_e32 v34, v34
	v_rcp_f32_e32 v35, v35
	v_exp_f32_e32 v38, v38
	v_exp_f32_e32 v36, v36
	v_exp_f32_e32 v37, v37
	v_cvt_pk_bf16_f32 v34, v34, v35
	v_min_f32_e32 v35, v40, v246
	v_add_f32_e32 v38, 1.0, v38
	v_exp_f32_e32 v35, v35
	v_add_f32_e32 v36, 1.0, v36
	v_add_f32_e32 v37, 1.0, v37
	v_rcp_f32_e32 v38, v38
	v_add_f32_e32 v35, 1.0, v35
	v_rcp_f32_e32 v35, v35
	v_rcp_f32_e32 v36, v36
	v_rcp_f32_e32 v37, v37
	v_cvt_pk_bf16_f32 v35, v35, v38
	v_min_f32_e32 v38, v43, v246
	v_cvt_pk_bf16_f32 v36, v36, v37
	v_min_f32_e32 v37, v42, v246
	v_exp_f32_e32 v38, v38
	v_exp_f32_e32 v37, v37
	v_add_f32_e32 v38, 1.0, v38
	v_add_f32_e32 v37, 1.0, v37
	v_rcp_f32_e32 v37, v37
	v_rcp_f32_e32 v38, v38
	s_nop 0
	v_cvt_pk_bf16_f32 v37, v37, v38
	global_store_dwordx4 v[90:91], v[34:37], off offset:3072
	s_nop 1
	v_mul_f32_e32 v34, 0xbfb8aa3b, v141
	v_pk_mul_f32 v[30:31], v[30:31], v[34:35] op_sel_hi:[1,0]
	v_pk_mul_f32 v[36:37], v[28:29], v[34:35] op_sel_hi:[1,0]
	v_min_f32_e32 v28, v30, v246
	v_min_f32_e32 v29, v31, v246
	v_pk_mul_f32 v[26:27], v[26:27], v[34:35] op_sel_hi:[1,0]
	v_exp_f32_e32 v28, v28
	v_exp_f32_e32 v29, v29
	v_pk_mul_f32 v[32:33], v[32:33], v[34:35] op_sel_hi:[1,0]
	v_min_f32_e32 v26, v26, v246
	v_add_f32_e32 v28, 1.0, v28
	v_add_f32_e32 v29, 1.0, v29
	v_rcp_f32_e32 v28, v28
	v_rcp_f32_e32 v29, v29
	v_min_f32_e32 v30, v33, v246
	v_min_f32_e32 v27, v27, v246
	v_exp_f32_e32 v26, v26
	v_cvt_pk_bf16_f32 v28, v28, v29
	v_min_f32_e32 v29, v32, v246
	v_exp_f32_e32 v30, v30
	v_exp_f32_e32 v29, v29
	v_exp_f32_e32 v27, v27
	v_add_f32_e32 v26, 1.0, v26
	v_add_f32_e32 v30, 1.0, v30
	v_add_f32_e32 v29, 1.0, v29
	v_add_f32_e32 v27, 1.0, v27
	v_rcp_f32_e32 v29, v29
	v_rcp_f32_e32 v30, v30
	v_rcp_f32_e32 v26, v26
	v_rcp_f32_e32 v27, v27
	v_pk_mul_f32 v[22:23], v[22:23], v[34:35] op_sel_hi:[1,0]
	v_cvt_pk_bf16_f32 v29, v29, v30
	v_pk_mul_f32 v[24:25], v[24:25], v[34:35] op_sel_hi:[1,0]
	v_cvt_pk_bf16_f32 v30, v26, v27
	v_min_f32_e32 v26, v36, v246
	v_min_f32_e32 v27, v37, v246
	s_nop 0
	v_exp_f32_e32 v26, v26
	v_exp_f32_e32 v27, v27
	v_add_f32_e32 v26, 1.0, v26
	v_add_f32_e32 v27, 1.0, v27
	v_rcp_f32_e32 v26, v26
	v_rcp_f32_e32 v27, v27
	s_nop 0
	v_cvt_pk_bf16_f32 v31, v26, v27
	v_add_co_u32_e32 v26, vcc, s0, v122
	s_mov_b64 s[0:1], -1
	s_nop 0
	v_addc_co_u32_e32 v27, vcc, 0, v123, vcc
	global_store_dwordx4 v[26:27], v[28:31], off
	s_andn2_b64 vcc, exec, s[38:39]
	s_nop 0
	v_pk_mul_f32 v[28:29], v[20:21], v[34:35] op_sel_hi:[1,0]
	v_pk_mul_f32 v[20:21], v[18:19], v[34:35] op_sel_hi:[1,0]
	v_min_f32_e32 v18, v22, v246
	v_min_f32_e32 v19, v23, v246
	v_min_f32_e32 v22, v25, v246
	s_nop 0
	v_exp_f32_e32 v18, v18
	v_exp_f32_e32 v19, v19
	v_min_f32_e32 v20, v20, v246
	v_min_f32_e32 v21, v21, v246
	v_add_f32_e32 v18, 1.0, v18
	v_add_f32_e32 v19, 1.0, v19
	v_rcp_f32_e32 v18, v18
	v_rcp_f32_e32 v19, v19
	v_exp_f32_e32 v22, v22
	v_exp_f32_e32 v20, v20
	v_exp_f32_e32 v21, v21
	v_cvt_pk_bf16_f32 v18, v18, v19
	v_min_f32_e32 v19, v24, v246
	v_add_f32_e32 v22, 1.0, v22
	v_exp_f32_e32 v19, v19
	v_add_f32_e32 v20, 1.0, v20
	v_add_f32_e32 v21, 1.0, v21
	v_rcp_f32_e32 v22, v22
	v_add_f32_e32 v19, 1.0, v19
	v_rcp_f32_e32 v19, v19
	v_rcp_f32_e32 v20, v20
	v_rcp_f32_e32 v21, v21
	v_cvt_pk_bf16_f32 v19, v19, v22
	v_min_f32_e32 v22, v29, v246
	v_cvt_pk_bf16_f32 v20, v20, v21
	v_min_f32_e32 v21, v28, v246
	v_exp_f32_e32 v22, v22
	v_exp_f32_e32 v21, v21
	v_add_f32_e32 v22, 1.0, v22
	v_add_f32_e32 v21, 1.0, v21
	v_rcp_f32_e32 v21, v21
	v_rcp_f32_e32 v22, v22
	s_nop 0
	v_cvt_pk_bf16_f32 v21, v21, v22
	global_store_dwordx4 v[26:27], v[18:21], off offset:1024
	s_nop 1
	v_mul_f32_e32 v18, 0xbfb8aa3b, v140
	v_pk_mul_f32 v[14:15], v[14:15], v[18:19] op_sel_hi:[1,0]
	v_pk_mul_f32 v[20:21], v[12:13], v[18:19] op_sel_hi:[1,0]
	v_pk_mul_f32 v[12:13], v[10:11], v[18:19] op_sel_hi:[1,0]
	v_min_f32_e32 v10, v14, v246
	v_min_f32_e32 v11, v15, v246
	v_pk_mul_f32 v[16:17], v[16:17], v[18:19] op_sel_hi:[1,0]
	v_exp_f32_e32 v10, v10
	v_exp_f32_e32 v11, v11
	v_min_f32_e32 v14, v17, v246
	v_min_f32_e32 v12, v12, v246
	v_add_f32_e32 v10, 1.0, v10
	v_add_f32_e32 v11, 1.0, v11
	v_rcp_f32_e32 v10, v10
	v_rcp_f32_e32 v11, v11
	v_min_f32_e32 v13, v13, v246
	v_exp_f32_e32 v14, v14
	v_exp_f32_e32 v12, v12
	v_cvt_pk_bf16_f32 v10, v10, v11
	v_min_f32_e32 v11, v16, v246
	v_exp_f32_e32 v13, v13
	v_exp_f32_e32 v11, v11
	v_add_f32_e32 v14, 1.0, v14
	v_add_f32_e32 v12, 1.0, v12
	v_add_f32_e32 v13, 1.0, v13
	v_add_f32_e32 v11, 1.0, v11
	v_rcp_f32_e32 v11, v11
	v_rcp_f32_e32 v14, v14
	v_rcp_f32_e32 v12, v12
	v_rcp_f32_e32 v13, v13
	v_pk_mul_f32 v[6:7], v[6:7], v[18:19] op_sel_hi:[1,0]
	v_cvt_pk_bf16_f32 v11, v11, v14
	v_min_f32_e32 v14, v21, v246
	v_cvt_pk_bf16_f32 v12, v12, v13
	v_min_f32_e32 v13, v20, v246
	v_exp_f32_e32 v14, v14
	v_exp_f32_e32 v13, v13
	v_pk_mul_f32 v[8:9], v[8:9], v[18:19] op_sel_hi:[1,0]
	v_add_f32_e32 v14, 1.0, v14
	v_add_f32_e32 v13, 1.0, v13
	v_rcp_f32_e32 v13, v13
	v_rcp_f32_e32 v14, v14
	s_nop 0
	v_cvt_pk_bf16_f32 v13, v13, v14
	global_store_dwordx4 v[26:27], v[10:13], off offset:2048
	s_nop 1
	v_pk_mul_f32 v[10:11], v[4:5], v[18:19] op_sel_hi:[1,0]
	v_pk_mul_f32 v[4:5], v[2:3], v[18:19] op_sel_hi:[1,0]
	v_min_f32_e32 v2, v6, v246
	v_min_f32_e32 v3, v7, v246
	v_min_f32_e32 v6, v9, v246
	s_nop 0
	v_exp_f32_e32 v2, v2
	v_exp_f32_e32 v3, v3
	v_min_f32_e32 v4, v4, v246
	v_min_f32_e32 v5, v5, v246
	v_add_f32_e32 v2, 1.0, v2
	v_add_f32_e32 v3, 1.0, v3
	v_rcp_f32_e32 v2, v2
	v_rcp_f32_e32 v3, v3
	v_exp_f32_e32 v6, v6
	v_exp_f32_e32 v4, v4
	v_exp_f32_e32 v5, v5
	v_cvt_pk_bf16_f32 v2, v2, v3
	v_min_f32_e32 v3, v8, v246
	v_add_f32_e32 v6, 1.0, v6
	v_exp_f32_e32 v3, v3
	v_add_f32_e32 v4, 1.0, v4
	v_add_f32_e32 v5, 1.0, v5
	v_rcp_f32_e32 v6, v6
	v_add_f32_e32 v3, 1.0, v3
	v_rcp_f32_e32 v3, v3
	v_rcp_f32_e32 v4, v4
	v_rcp_f32_e32 v5, v5
	v_cvt_pk_bf16_f32 v3, v3, v6
	v_min_f32_e32 v6, v11, v246
	v_cvt_pk_bf16_f32 v4, v4, v5
	v_min_f32_e32 v5, v10, v246
	v_exp_f32_e32 v6, v6
	v_exp_f32_e32 v5, v5
	v_add_f32_e32 v6, 1.0, v6
	v_add_f32_e32 v5, 1.0, v5
	v_rcp_f32_e32 v5, v5
	v_rcp_f32_e32 v6, v6
	s_nop 0
	v_cvt_pk_bf16_f32 v5, v5, v6
	global_store_dwordx4 v[26:27], v[2:5], off offset:3072
	s_cbranch_vccnz .LBB0_328
	s_andn2_b64 vcc, exec, s[6:7]
	s_cbranch_vccnz .LBB0_327
	s_barrier
	s_branch .LBB0_327

; template <int NP> __device__ __forceinline__ void row_scales(float (&rs)[2][4], const float* base, long row0, int fq, float inv_n) {
;     float t[2][4];
; #pragma unroll
;     for (int ai = 0; ai < 2; ++ai)
; #pragma unroll
;         for (int m = 0; m < 4; ++m) { const long row = row0 + ai * 128 + m * 16;
;             if (NP == 16) { const f32x4 v = *(const f32x4*)(base + row * 16 + 4 * fq); t[ai][m] = (v.x + v.y) + (v.z + v.w); }
;             else if (NP == 8) { const f32x2 v = *(const f32x2*)(base + row * 8 + 2 * fq); t[ai][m] = v.x + v.y; }
;             else t[ai][m] = base[row * 4 + fq]; }
; #pragma unroll
;     for (int ai = 0; ai < 2; ++ai)
; #pragma unroll
;         for (int m = 0; m < 4; ++m) rs[ai][m] = rsqrtf(red_fq(t[ai][m]) * inv_n + EPS);
;     __device__ __forceinline__ void operator()(AccT& acc, const Unit& u, int wr, int wc, int fr, int fq, LAS unsigned char*) const {
;         const long row0 = (long)u.pm * 256 + wr * 64 + fr;
;         float rsa[2][4]; row_scales<16>(rsa, ssqx, row0, fq, 1.f / 1024.f);
; #pragma unroll
;         for (int ai = 0; ai < 2; ++ai)
; #pragma unroll
;             for (int m = 0; m < 4; ++m) {
;                 const long row = row0 + ai * 128 + m * 16;
;                 const float rs = rsa[ai][m];
;                 f32x4 v[2][2];
; #pragma unroll
;                 for (int bj = 0; bj < 2; ++bj)
; #pragma unroll
;                     for (int n = 0; n < 2; ++n) v[bj][n] = acc[ai][bj][m][n] * rs;
;                 const int cl = wc * 32 + 8 * fq;
;                 if (u.pn == 0 || u.pn == 2 || u.pn == 5 || u.pn == 6) {
.LBB0_640:
	s_ashr_i32 s1, s0, 31
	s_lshl_b64 s[0:1], s[0:1], 8
	v_lshl_add_u64 v[156:157], s[0:1], 0, v[136:137]
	v_lshlrev_b64 v[176:177], 6, v[156:157]
	v_lshl_add_u64 v[170:171], v[144:145], 0, v[176:177]
	global_load_dwordx4 v[158:161], v[170:171], off
	s_movk_i32 s0, 0x2000
	v_add_co_u32_e32 v178, vcc, s0, v170
	s_mov_b32 s0, 0x3a800000
	s_nop 0
	v_addc_co_u32_e32 v179, vcc, 0, v171, vcc
	global_load_dwordx4 v[208:211], v[170:171], off offset:1024
	global_load_dwordx4 v[212:215], v[170:171], off offset:2048
	global_load_dwordx4 v[216:219], v[170:171], off offset:3072
	global_load_dwordx4 v[220:223], v[178:179], off
	global_load_dwordx4 v[224:227], v[178:179], off offset:1024
	global_load_dwordx4 v[228:231], v[178:179], off offset:2048
	global_load_dwordx4 v[232:235], v[178:179], off offset:3072
	s_cmp_lg_u32 s18, 0
	s_cselect_b64 s[16:17], -1, 0
	s_cmp_eq_u32 s18, 3
	s_cselect_b64 s[42:43], -1, 0
	s_mov_b64 s[8:9], -1
	s_mov_b64 s[22:23], 0
	s_cmp_lt_i32 s18, 2
	s_mov_b64 s[12:13], 0
	s_mov_b64 s[78:79], 0
	s_waitcnt vmcnt(0)
	v_mov_b32_e32 v162, v159
	v_mov_b32_e32 v163, v160
	v_mov_b32_e32 v159, v161
	v_pk_add_f32 v[158:159], v[162:163], v[158:159]
	s_nop 0
	v_pk_add_f32 v[162:163], v[158:159], v[158:159] op_sel:[0,1] op_sel_hi:[1,0]
	v_mov_b64_e32 v[158:159], v[208:209]
	v_mov_b64_e32 v[160:161], v[210:211]
	v_mov_b32_e32 v0, v162
	s_nop 1
	v_permlane16_swap_b32_e32 v162, v0
	v_mov_b32_e32 v164, v159
	v_mov_b32_e32 v165, v160
	v_mov_b32_e32 v159, v161
	v_pk_add_f32 v[158:159], v[164:165], v[158:159]
	s_nop 0
	v_pk_add_f32 v[166:167], v[158:159], v[158:159] op_sel:[0,1] op_sel_hi:[1,0]
	v_mov_b64_e32 v[158:159], v[212:213]
	v_mov_b64_e32 v[160:161], v[214:215]
	v_mov_b32_e32 v164, v159
	v_mov_b32_e32 v165, v160
	v_mov_b32_e32 v159, v161
	v_pk_add_f32 v[158:159], v[164:165], v[158:159]
	s_nop 0
	v_pk_add_f32 v[168:169], v[158:159], v[158:159] op_sel:[0,1] op_sel_hi:[1,0]
	v_mov_b64_e32 v[158:159], v[216:217]
	v_mov_b64_e32 v[160:161], v[218:219]
	v_mov_b32_e32 v164, v159
	v_mov_b32_e32 v165, v160
	v_mov_b32_e32 v159, v161
	v_pk_add_f32 v[158:159], v[164:165], v[158:159]
	s_nop 0
	v_pk_add_f32 v[164:165], v[158:159], v[158:159] op_sel:[0,1] op_sel_hi:[1,0]
	v_mov_b64_e32 v[158:159], v[220:221]
	v_mov_b64_e32 v[160:161], v[222:223]
	v_mov_b32_e32 v170, v159
	v_mov_b32_e32 v171, v160
	v_mov_b32_e32 v159, v161
	v_pk_add_f32 v[158:159], v[170:171], v[158:159]
	s_nop 0
	v_pk_add_f32 v[170:171], v[158:159], v[158:159] op_sel:[0,1] op_sel_hi:[1,0]
	v_mov_b64_e32 v[158:159], v[224:225]
	v_mov_b64_e32 v[160:161], v[226:227]
	v_mov_b32_e32 v172, v159
	v_mov_b32_e32 v173, v160
	v_mov_b32_e32 v159, v161
	v_pk_add_f32 v[158:159], v[172:173], v[158:159]
	v_mov_b64_e32 v[172:173], v[228:229]
	v_mov_b64_e32 v[174:175], v[230:231]
	v_pk_add_f32 v[158:159], v[158:159], v[158:159] op_sel:[0,1] op_sel_hi:[1,0]
	v_mov_b32_e32 v160, v173
	v_mov_b32_e32 v161, v174
	v_mov_b32_e32 v173, v175
	v_pk_add_f32 v[160:161], v[160:161], v[172:173]
	v_mov_b64_e32 v[172:173], v[232:233]
	v_mov_b64_e32 v[174:175], v[234:235]
	v_pk_add_f32 v[160:161], v[160:161], v[160:161] op_sel:[0,1] op_sel_hi:[1,0]
	v_mov_b32_e32 v178, v173
	v_mov_b32_e32 v179, v174
	v_mov_b32_e32 v173, v175
	v_pk_add_f32 v[172:173], v[178:179], v[172:173]
	s_nop 0
	v_pk_add_f32 v[178:179], v[172:173], v[172:173] op_sel:[0,1] op_sel_hi:[1,0]
	v_add_f32_e32 v173, v162, v0
	v_mov_b32_e32 v0, v166
	s_nop 1
	v_permlane16_swap_b32_e32 v166, v0
	v_add_f32_e32 v172, v166, v0
	v_mov_b32_e32 v0, v168
	s_nop 1
	v_permlane16_swap_b32_e32 v168, v0
	v_add_f32_e32 v167, v168, v0
	v_mov_b32_e32 v0, v164
	s_nop 1
	v_permlane16_swap_b32_e32 v164, v0
	v_add_f32_e32 v166, v164, v0
	v_mov_b32_e32 v0, v170
	s_nop 1
	v_permlane16_swap_b32_e32 v170, v0
	v_add_f32_e32 v163, v170, v0
	v_mov_b32_e32 v0, v158
	s_nop 1
	v_permlane16_swap_b32_e32 v158, v0
	v_add_f32_e32 v162, v158, v0
	v_mov_b32_e32 v0, v160
	s_nop 1
	v_permlane16_swap_b32_e32 v160, v0
	v_mov_b32_e32 v175, v173
	v_mov_b32_e32 v174, v172
	v_add_f32_e32 v159, v160, v0
	v_mov_b32_e32 v0, v178
	v_permlane32_swap_b32_e32 v173, v175
	v_permlane32_swap_b32_e32 v172, v174
	v_permlane16_swap_b32_e32 v178, v0
	v_add_f32_e32 v158, v178, v0
	v_pk_add_f32 v[170:171], v[172:173], v[174:175]
	v_mov_b32_e32 v169, v167
	v_mov_b32_e32 v168, v166
	v_mov_b32_e32 v165, v163
	v_mov_b32_e32 v164, v162
	v_mov_b32_e32 v161, v159
	v_mov_b32_e32 v160, v158
	v_pk_fma_f32 v[170:171], v[170:171], s[0:1], v[194:195] op_sel_hi:[1,0,0]
	v_permlane32_swap_b32_e32 v167, v169
	v_permlane32_swap_b32_e32 v166, v168
	v_permlane32_swap_b32_e32 v163, v165
	v_permlane32_swap_b32_e32 v162, v164
	v_permlane32_swap_b32_e32 v159, v161
	v_permlane32_swap_b32_e32 v158, v160
	v_cmp_gt_f32_e64 s[44:45], s33, v170
	v_cmp_gt_f32_e64 s[0:1], s33, v171
	s_cbranch_scc1 .LBB0_653
	s_cmp_gt_i32 s18, 4
	s_cbranch_scc0 .LBB0_647
	s_cmp_gt_i32 s18, 5
	s_cbranch_scc0 .LBB0_648
	s_mov_b64 s[78:79], -1
	s_mov_b64 s[8:9], 0
	s_cmp_eq_u32 s18, 6
	s_cbranch_scc0 .LBB0_645
	v_readlane_b32 s12, v255, 48
	v_lshlrev_b64 v[172:173], 9, v[156:157]
	v_readlane_b32 s13, v255, 49
	s_mov_b64 s[78:79], 0
	s_nop 0
	v_lshl_add_u64 v[172:173], s[12:13], 0, v[172:173]
	s_mov_b64 s[12:13], -1
